# MLA loop: next tile stored to LDS at the top of the iteration (register prefetch distance 2), end of iteration is only lgkmcnt(0)+barrier
# speedup vs baseline: 1.3076x; 1.0009x over previous
; #define GLOAD(t) { const int pos0_ = TILE_POS(t); \
;     rk0 = *(const uint4*)(K + (size_t)(pos0_ + kr0) * ldk + kc0); rk1 = *(const uint4*)(K + (size_t)(pos0_ + kr1) * ldk + kc1); \
;     if (NKC == 3) rk2 = *(const uint4*)(K + (size_t)(pos0_ + kr2) * ldk + kc2); \
;     rv0 = *(const uint4*)(Vt + (size_t)vd0 * SEQA + pos0_ + vk0); rv1 = *(const uint4*)(Vt + (size_t)(vd0 + 32) * SEQA + pos0_ + vk0); }
; #define LSTORE(bf) { *(uint4*)&Ks[bf][kr0][kc0] = rk0; *(uint4*)&Ks[bf][kr1][kc1] = rk1; if (NKC == 3) *(uint4*)&Ks[bf][kr2][kc2] = rk2; \
;     *(uint2*)&Vs[bf][vd0][vk0] = make_uint2(rv0.x, rv0.y); *(uint2*)&Vs[bf][vd0][vk0 + 4] = make_uint2(rv0.z, rv0.w); \
;     *(uint2*)&Vs[bf][vd0 + 32][vk0] = make_uint2(rv1.x, rv1.y); *(uint2*)&Vs[bf][vd0 + 32][vk0 + 4] = make_uint2(rv1.z, rv1.w); }
; #define GLOAD(t) { const int pos0_ = (t) * 64; \
;     rk0 = *(const uint4*)(K + (size_t)(pos0_ + kr0) * ldk + kc0); rk1 = *(const uint4*)(K + (size_t)(pos0_ + kr1) * ldk + kc1); \
;     if (NKC == 3) rk2 = *(const uint4*)(K + (size_t)(pos0_ + kr2) * ldk + kc2); \
;     rv0 = *(const uint4*)(Vt + (size_t)vd0 * SEQA + pos0_ + vk0); rv1 = *(const uint4*)(Vt + (size_t)(vd0 + 32) * SEQA + pos0_ + vk0); }
; #define LSTORE(bf) { *(uint4*)&Ks[bf][kr0][kc0] = rk0; *(uint4*)&Ks[bf][kr1][kc1] = rk1; if (NKC == 3) *(uint4*)&Ks[bf][kr2][kc2] = rk2; \
;     *(uint2*)&Vs[bf][vd0][vk0] = make_uint2(rv0.x, rv0.y); *(uint2*)&Vs[bf][vd0][vk0 + 4] = make_uint2(rv0.z, rv0.w); \
;     *(uint2*)&Vs[bf][vd0 + 32][vk0] = make_uint2(rv1.x, rv1.y); *(uint2*)&Vs[bf][vd0 + 32][vk0 + 4] = make_uint2(rv1.z, rv1.w); }
; template <int DK, bool NA> ...
;     ...
;   const int kr0 = tid / KCH, kc0 = (tid % KCH) * 8, kr1 = (tid + 256) / KCH, kc1 = ((tid + 256) % KCH) * 8, kr2 = (tid + 512) / KCH, kc2 = ((tid + 512) % KCH) * 8;
;   const int vd0 = tid >> 3, vk0 = (tid & 7) * 8;
;     ...
;   GLOAD(0); LSTORE(0);
;   __syncthreads();
;   for (int t = 0; t < nTiles; t++) {
;     const int buf = t & 1;
;     if (t + 1 < nTiles) GLOAD(t + 1);
.LBB0_889:
	v_cmp_gt_i32_e32 vcc, s11, v0
	s_and_saveexec_b64 s[2:3], vcc
	s_xor_b64 s[2:3], exec, s[2:3]
	v_ashrrev_i32_e32 v2, 7, v0
	s_or_saveexec_b64 s[6:7], s[2:3]
	v_mov_b64_e32 v[4:5], 0x100
	v_mov_b32_e32 v5, 0x42
	v_mov_b32_e32 v3, 31
	v_mov_b32_e32 v6, 5
	s_mov_b64 s[12:13], 0x3000
	s_xor_b64 exec, exec, s[6:7]
	v_add_u32_e32 v2, 0xfffffc00, v0
	v_mov_b64_e32 v[4:5], 0
	v_lshrrev_b32_e32 v2, 3, v2
	v_mov_b32_e32 v5, 2
	v_mov_b32_e32 v6, 1
	v_mov_b32_e32 v3, 1
	s_or_b64 exec, exec, s[6:7]
	v_and_b32_e32 v7, v3, v0
	v_ashrrev_i32_e32 v3, 31, v2
	v_bfe_u32 v147, v0, v6, 2
	v_lshl_add_u32 v0, v7, 7, v4
	s_movk_i32 s2, 0x1100
	v_lshlrev_b64 v[8:9], 2, v[2:3]
	v_mad_i64_i32 v[158:159], s[2:3], v2, s2, v[0:1]
	v_or_b32_e32 v0, v8, v147
	v_mov_b64_e32 v[10:11], s[36:37]
	v_mad_u64_u32 v[18:19], s[2:3], v0, s48, v[10:11]
	v_mov_b64_e32 v[10:11], s[38:39]
	v_mov_b64_e32 v[6:7], s[34:35]
	v_mad_i32_i24 v19, v9, s48, v19
	v_mad_u64_u32 v[20:21], s[2:3], v0, s14, v[10:11]
	v_mad_i32_i24 v21, v9, s14, v21
	v_lshl_add_u64 v[8:9], v[18:19], 0, v[120:121]
	v_lshl_add_u64 v[10:11], v[18:19], 0, v[122:123]
	v_mad_u64_u32 v[6:7], s[2:3], v158, s24, v[6:7]
	v_mul_u32_u24_e32 v0, 0x60, v147
	v_lshl_add_u64 v[8:9], v[114:115], 1, v[8:9]
	v_lshl_add_u64 v[14:15], v[116:117], 1, v[10:11]
	v_mad_i32_i24 v7, v159, s24, v7
	v_lshlrev_b32_e32 v0, 1, v0
	s_barrier
	global_load_dwordx4 v[10:13], v[8:9], off
	s_nop 0
	global_load_dwordx4 v[14:17], v[14:15], off
	v_lshl_add_u64 v[8:9], v[18:19], 0, v[124:125]
	v_lshl_add_u64 v[18:19], v[20:21], 0, v[126:127]
	v_mov_b32_e32 v145, v1
	v_lshl_add_u64 v[6:7], v[6:7], 0, v[0:1]
	v_lshl_add_u64 v[22:23], v[18:19], 0, v[144:145]
	v_lshl_add_u64 v[18:19], v[20:21], 0, v[128:129]
	v_lshl_add_u64 v[6:7], v[6:7], 0, v[112:113]
	v_mov_b32_e32 v143, v1
	v_lshl_add_u64 v[8:9], v[118:119], 1, v[8:9]
	v_lshl_add_u64 v[26:27], v[18:19], 0, v[144:145]
	v_lshl_add_u64 v[6:7], v[6:7], 0, v[142:143]
	global_load_dwordx4 v[18:21], v[8:9], off
	s_nop 0
	global_load_dwordx4 v[22:25], v[22:23], off
	s_nop 0
	global_load_dwordx4 v[26:29], v[26:27], off
	s_nop 0
	global_load_dwordx4 v[100:103], v[6:7], off
	global_load_dwordx4 v[96:99], v[6:7], off offset:32
	global_load_dwordx4 v[92:95], v[6:7], off offset:64
	global_load_dwordx4 v[88:91], v[6:7], off offset:96
	global_load_dwordx4 v[84:87], v[6:7], off offset:128
	global_load_dwordx4 v[80:83], v[6:7], off offset:160
	s_mov_b32 s2, 0x220000
	v_add_u32_e32 v38, 0x6800, v171
	v_add_u32_e32 v39, 0x7900, v171
	v_mad_i64_i32 v[30:31], s[2:3], v2, s2, v[134:135]
	v_mad_i64_i32 v[32:33], s[2:3], v2, s15, v[136:137]
	v_mad_i64_i32 v[34:35], s[2:3], v2, s15, v[138:139]
	v_mad_i64_i32 v[36:37], s[2:3], v2, s15, v[140:141]
	v_add_u32_e32 v177, 1, v5
	v_mov_b32_e32 v2, v1
	v_mov_b32_e32 v3, v1
	v_mov_b32_e32 v4, v1
	v_mov_b32_e32 v5, v1
	v_mov_b32_e32 v6, v1
	v_mov_b32_e32 v7, v1
	v_mov_b32_e32 v8, v1
	v_mov_b32_e32 v9, v1
	v_mad_u64_u32 v[160:161], s[6:7], v147, s14, v[30:31]
	v_mad_u64_u32 v[162:163], s[6:7], v147, s48, v[32:33]
	v_mad_u64_u32 v[164:165], s[6:7], v147, s48, v[34:35]
	v_mad_u64_u32 v[166:167], s[6:7], v147, s48, v[36:37]
	v_mov_b32_e32 v0, v1
	s_mov_b32 s2, 0
	v_mov_b32_e32 v143, 0
	v_mov_b32_e32 v145, 0xf149f2ca
	s_mov_b64 s[6:7], 0
	s_waitcnt vmcnt(10)
	ds_write_b128 v151, v[10:13]
	s_waitcnt vmcnt(9)
	ds_write_b128 v157, v[14:17]
	s_waitcnt vmcnt(8)
	ds_write_b128 v169, v[18:21]
	s_waitcnt vmcnt(7)
	ds_write2_b64 v38, v[22:23], v[24:25] offset1:1
	s_waitcnt vmcnt(6)
	ds_write2_b64 v39, v[26:27], v[28:29] offset1:1
	v_mov_b32_e32 v14, v1
	v_mov_b32_e32 v15, v1
	v_mov_b32_e32 v10, v1
	v_mov_b32_e32 v11, v1
	v_mov_b32_e32 v12, v1
	v_mov_b32_e32 v13, v1
	v_mov_b64_e32 v[30:31], v[14:15]
	v_mov_b64_e32 v[46:47], v[14:15]
	v_mov_b64_e32 v[28:29], v[12:13]
	v_mov_b64_e32 v[26:27], v[10:11]
	v_mov_b64_e32 v[24:25], v[8:9]
	v_mov_b64_e32 v[22:23], v[6:7]
	v_mov_b64_e32 v[20:21], v[4:5]
	v_mov_b64_e32 v[18:19], v[2:3]
	v_mov_b64_e32 v[16:17], v[0:1]
	v_mov_b64_e32 v[44:45], v[12:13]
	v_mov_b64_e32 v[42:43], v[10:11]
	v_mov_b64_e32 v[40:41], v[8:9]
	v_mov_b64_e32 v[38:39], v[6:7]
	v_mov_b64_e32 v[36:37], v[4:5]
	v_mov_b64_e32 v[34:35], v[2:3]
	v_mov_b64_e32 v[32:33], v[0:1]
	s_waitcnt lgkmcnt(0)
	s_barrier
	v_mov_b32_e32 v224, 0
	v_mov_b32_e32 v225, 0
	v_mov_b32_e32 v226, 0
	v_mov_b32_e32 v227, 0
	v_mov_b32_e32 v228, 0
	v_mov_b32_e32 v229, 0
	v_mov_b32_e32 v230, 0
	v_mov_b32_e32 v231, 0
	v_mov_b32_e32 v232, 0
	v_mov_b32_e32 v233, 0
	v_mov_b32_e32 v234, 0
	v_mov_b32_e32 v235, 0
	v_mov_b32_e32 v236, 0
	v_mov_b32_e32 v237, 0
	v_mov_b32_e32 v238, 0
	v_mov_b32_e32 v239, 0
	v_mov_b32_e32 v204, 0
	v_lshl_add_u64 v[162:163], s[96:97], 0, v[162:163]
	v_lshl_add_u64 v[166:167], s[96:97], 0, v[166:167]
	v_lshl_add_u64 v[164:165], s[96:97], 0, v[164:165]
	v_lshl_add_u64 v[160:161], s[96:97], 0, v[160:161]
	s_mov_b32 s8, 0x12323000
	s_mov_b32 s9, 0
	v_lshl_add_u64 v[164:165], s[8:9], 0, v[164:165]
	s_mov_b32 s8, 0x13ce4000
	v_lshl_add_u64 v[184:185], s[8:9], 0, v[160:161]
	s_mov_b32 s8, 0x13ca0000
	v_lshl_add_u64 v[160:161], s[8:9], 0, v[160:161]
	global_load_dwordx4 v[2:5], v[162:163], off
	global_load_dwordx4 v[6:9], v[166:167], off
	global_load_dwordx4 v[10:13], v[164:165], off
	global_load_dwordx4 v[108:111], v[184:185], off offset:128
	global_load_dwordx4 v[104:107], v[160:161], off offset:128
	s_mov_b64 s[8:9], 0x80
	v_lshl_add_u64 v[162:163], v[162:163], 0, s[12:13]
	v_lshl_add_u64 v[164:165], v[164:165], 0, s[12:13]
	v_lshl_add_u64 v[166:167], v[166:167], 0, s[12:13]
	v_lshl_add_u64 v[160:161], v[160:161], 0, s[8:9]
	v_lshl_add_u64 v[184:185], v[184:185], 0, s[8:9]
	s_branch .LBB0_895
; #define GLOAD(t) { const int pos0_ = TILE_POS(t); \
;     rk0 = *(const uint4*)(K + (size_t)(pos0_ + kr0) * ldk + kc0); rk1 = *(const uint4*)(K + (size_t)(pos0_ + kr1) * ldk + kc1); \
;     if (NKC == 3) rk2 = *(const uint4*)(K + (size_t)(pos0_ + kr2) * ldk + kc2); \
;     rv0 = *(const uint4*)(Vt + (size_t)vd0 * SEQA + pos0_ + vk0); rv1 = *(const uint4*)(Vt + (size_t)(vd0 + 32) * SEQA + pos0_ + vk0); }
; #define LSTORE(bf) { *(uint4*)&Ks[bf][kr0][kc0] = rk0; *(uint4*)&Ks[bf][kr1][kc1] = rk1; if (NKC == 3) *(uint4*)&Ks[bf][kr2][kc2] = rk2; \
;     *(uint2*)&Vs[bf][vd0][vk0] = make_uint2(rv0.x, rv0.y); *(uint2*)&Vs[bf][vd0][vk0 + 4] = make_uint2(rv0.z, rv0.w); \
;     *(uint2*)&Vs[bf][vd0 + 32][vk0] = make_uint2(rv1.x, rv1.y); *(uint2*)&Vs[bf][vd0 + 32][vk0 + 4] = make_uint2(rv1.z, rv1.w); }
; #define GLOAD(t) { const int pos0_ = (t) * 64; \
;     rk0 = *(const uint4*)(K + (size_t)(pos0_ + kr0) * ldk + kc0); rk1 = *(const uint4*)(K + (size_t)(pos0_ + kr1) * ldk + kc1); \
;     if (NKC == 3) rk2 = *(const uint4*)(K + (size_t)(pos0_ + kr2) * ldk + kc2); \
;     rv0 = *(const uint4*)(Vt + (size_t)vd0 * SEQA + pos0_ + vk0); rv1 = *(const uint4*)(Vt + (size_t)(vd0 + 32) * SEQA + pos0_ + vk0); }
; #define LSTORE(bf) { *(uint4*)&Ks[bf][kr0][kc0] = rk0; *(uint4*)&Ks[bf][kr1][kc1] = rk1; if (NKC == 3) *(uint4*)&Ks[bf][kr2][kc2] = rk2; \
;     *(uint2*)&Vs[bf][vd0][vk0] = make_uint2(rv0.x, rv0.y); *(uint2*)&Vs[bf][vd0][vk0 + 4] = make_uint2(rv0.z, rv0.w); \
;     *(uint2*)&Vs[bf][vd0 + 32][vk0] = make_uint2(rv1.x, rv1.y); *(uint2*)&Vs[bf][vd0 + 32][vk0 + 4] = make_uint2(rv1.z, rv1.w); }
; template <int DK, bool NA> ...
;     ...
;   for (int t = 0; t < nTiles; t++) {
;     const int buf = t & 1;
;     if (t + 1 < nTiles) GLOAD(t + 1);
;     ...
;           }
;     }
;     if (t + 1 < nTiles) LSTORE(buf ^ 1);
;     __syncthreads();
;   }
.LBB0_894:
	s_mul_i32 s8, s3, 0x2200
	v_add_u32_e32 v0, s8, v173
	v_add_u32_e32 v15, 0x6800, v0
	v_add_u32_e32 v0, 0x7800, v0
	ds_read2_b64 v[240:243], v15 offset0:0 offset1:2
	ds_read2_b64 v[244:247], v0 offset0:32 offset1:34
	ds_read2_b64 v[248:251], v15 offset0:4 offset1:6
	ds_read2_b64 v[178:181], v0 offset0:36 offset1:38
	v_exp_f32_e32 v64, v64
	v_exp_f32_e32 v65, v65
	v_exp_f32_e32 v66, v66
	v_exp_f32_e32 v67, v67
	v_exp_f32_e32 v68, v68
	v_exp_f32_e32 v69, v69
	v_exp_f32_e32 v70, v70
	v_exp_f32_e32 v71, v71
	v_cvt_pk_bf16_f32 v188, v64, v65
	v_cvt_pk_bf16_f32 v189, v66, v67
	v_cvt_pk_bf16_f32 v190, v68, v69
	v_cvt_pk_bf16_f32 v191, v70, v71
	v_add_f32_e32 v14, v64, v65
	v_add_f32_e32 v14, v66, v14
	v_add_f32_e32 v14, v67, v14
	v_add_f32_e32 v14, v68, v14
	v_add_f32_e32 v14, v69, v14
	v_add_f32_e32 v14, v70, v14
	v_add_f32_e32 v14, v71, v14
	ds_read2_b64 v[64:67], v15 offset0:8 offset1:10
	ds_read2_b64 v[68:71], v0 offset0:40 offset1:42
	s_waitcnt lgkmcnt(4)
	v_mfma_f32_32x32x16_bf16 v[32:47], v[240:243], v[188:191], v[32:47]
	v_exp_f32_e32 v72, v72
	v_exp_f32_e32 v73, v73
	v_exp_f32_e32 v74, v74
	v_exp_f32_e32 v75, v75
	v_exp_f32_e32 v76, v76
	v_exp_f32_e32 v77, v77
	v_exp_f32_e32 v78, v78
	v_exp_f32_e32 v79, v79
	v_cvt_pk_bf16_f32 v192, v72, v73
	v_cvt_pk_bf16_f32 v193, v74, v75
	v_mfma_f32_32x32x16_bf16 v[16:31], v[244:247], v[188:191], v[16:31]
	v_cvt_pk_bf16_f32 v194, v76, v77
	v_cvt_pk_bf16_f32 v195, v78, v79
	v_add_f32_e32 v14, v72, v14
	v_add_f32_e32 v14, v73, v14
	v_add_f32_e32 v14, v74, v14
	v_add_f32_e32 v14, v75, v14
	v_add_f32_e32 v14, v76, v14
	v_add_f32_e32 v14, v77, v14
	v_add_f32_e32 v14, v78, v14
	v_add_f32_e32 v14, v79, v14
	ds_read2_b64 v[72:75], v15 offset0:12 offset1:14
	ds_read2_b64 v[76:79], v0 offset0:44 offset1:46
	s_waitcnt lgkmcnt(4)
	v_mfma_f32_32x32x16_bf16 v[32:47], v[248:251], v[192:195], v[32:47]
	v_exp_f32_e32 v48, v48
	v_exp_f32_e32 v49, v49
	v_exp_f32_e32 v50, v50
	v_exp_f32_e32 v51, v51
	v_exp_f32_e32 v52, v52
	v_exp_f32_e32 v53, v53
	v_exp_f32_e32 v54, v54
	v_exp_f32_e32 v55, v55
	v_cvt_pk_bf16_f32 v196, v48, v49
	v_cvt_pk_bf16_f32 v197, v50, v51
	v_mfma_f32_32x32x16_bf16 v[16:31], v[178:181], v[192:195], v[16:31]
	v_cvt_pk_bf16_f32 v198, v52, v53
	v_cvt_pk_bf16_f32 v199, v54, v55
	v_add_f32_e32 v14, v48, v14
	v_add_f32_e32 v14, v49, v14
	v_add_f32_e32 v14, v50, v14
	v_add_f32_e32 v14, v51, v14
	v_add_f32_e32 v14, v52, v14
	v_add_f32_e32 v14, v53, v14
	v_add_f32_e32 v14, v54, v14
	v_add_f32_e32 v14, v55, v14
	s_waitcnt lgkmcnt(2)
	v_mfma_f32_32x32x16_bf16 v[32:47], v[64:67], v[196:199], v[32:47]
	v_exp_f32_e32 v56, v56
	v_exp_f32_e32 v57, v57
	v_exp_f32_e32 v58, v58
	v_exp_f32_e32 v59, v59
	v_exp_f32_e32 v60, v60
	v_exp_f32_e32 v61, v61
	v_exp_f32_e32 v62, v62
	v_exp_f32_e32 v63, v63
	v_cvt_pk_bf16_f32 v200, v56, v57
	v_cvt_pk_bf16_f32 v201, v58, v59
	v_mfma_f32_32x32x16_bf16 v[16:31], v[68:71], v[196:199], v[16:31]
	v_cvt_pk_bf16_f32 v202, v60, v61
	v_cvt_pk_bf16_f32 v203, v62, v63
	v_add_f32_e32 v14, v56, v14
	v_add_f32_e32 v14, v57, v14
	v_add_f32_e32 v14, v58, v14
	v_add_f32_e32 v14, v59, v14
	v_add_f32_e32 v14, v60, v14
	v_add_f32_e32 v14, v61, v14
	v_add_f32_e32 v14, v62, v14
	v_add_f32_e32 v14, v63, v14
	s_waitcnt lgkmcnt(0)
	v_mfma_f32_32x32x16_bf16 v[32:47], v[72:75], v[200:203], v[32:47]
	v_mfma_f32_32x32x16_bf16 v[16:31], v[76:79], v[200:203], v[16:31]
	v_add_f32_e32 v143, v143, v14
	s_add_i32 s2, s2, 1
	v_cmp_eq_u32_e32 vcc, s2, v177
	s_or_b64 s[6:7], vcc, s[6:7]
	s_waitcnt lgkmcnt(0)
	s_barrier
	s_andn2_b64 exec, exec, s[6:7]
	s_cbranch_execz .LBB0_897
.LBB0_895:
	s_and_b32 s3, s2, 1
	s_xor_b32 s9, s3, 1
	s_mul_i32 s8, s9, 0x3400
	s_mulk_i32 s9, 0x2200
	v_add3_u32 v0, s8, v149, v174
	s_waitcnt vmcnt(4)
	ds_write_b128 v0, v[2:5]
	v_add3_u32 v0, s8, v153, v175
	s_waitcnt vmcnt(3)
	ds_write_b128 v0, v[6:9]
	v_add3_u32 v0, s8, v168, v176
	s_waitcnt vmcnt(2)
	ds_write_b128 v0, v[10:13]
	v_add3_u32 v0, s9, v170, v144
	v_add_u32_e32 v14, 0x6800, v0
	v_add_u32_e32 v0, 0x7900, v0
	s_waitcnt vmcnt(0)
	ds_write2_b64 v14, v[104:105], v[106:107] offset1:1
	ds_write2_b64 v0, v[108:109], v[110:111] offset1:1
	s_add_i32 s8, s2, 1
	v_cmp_lt_u32_e32 vcc, s8, v177
	s_cbranch_vccz .Lb_nofetch
	global_load_dwordx4 v[2:5], v[162:163], off
	global_load_dwordx4 v[6:9], v[166:167], off
	global_load_dwordx4 v[10:13], v[164:165], off
	global_load_dwordx4 v[108:111], v[184:185], off offset:128
	global_load_dwordx4 v[104:107], v[160:161], off offset:128
	s_mov_b64 s[8:9], 0x80
	v_lshl_add_u64 v[162:163], v[162:163], 0, s[12:13]
	v_lshl_add_u64 v[164:165], v[164:165], 0, s[12:13]
	v_lshl_add_u64 v[166:167], v[166:167], 0, s[12:13]
	v_lshl_add_u64 v[160:161], v[160:161], 0, s[8:9]
	v_lshl_add_u64 v[184:185], v[184:185], 0, s[8:9]
; #define MFMA(a, b, c) __builtin_amdgcn_mfma_f32_32x32x16_bf16((a), (b), (c), 0, 0, 0)
; DI float xhalf_max(float v) { auto r = __builtin_amdgcn_permlane32_swap(__float_as_uint(v), __float_as_uint(v), false, false); return fmaxf(__uint_as_float(r[0]), __uint_as_float(r[1])); }
; template <int DK, bool NA> ...
;     ...
;     if (act) {
;       f32x16 s[2];
; #pragma unroll
;       for (int kb = 0; kb < 2; kb++) {
; #pragma unroll
;         for (int i = 0; i < 16; i++) s[kb][i] = 0.f;
; #pragma unroll
;         for (int ks = 0; ks < KS; ks++) { bf16x8 a = *(const bf16x8*)&Ks[buf][kb * 32 + r][ks * 16 + h * 8]; s[kb] = MFMA(a, qf[ks], s[kb]); }
;       }
;       float mx = -1e30f;
; #pragma unroll
;       for (int kb = 0; kb < 2; kb++)
; #pragma unroll
;         for (int i = 0; i < 16; i++) {
;           float v = s[kb][i];
;           if (NA) {
;             if (win) {
;               const int kc = kb * 32 + (i & 3) + 8 * (i >> 2) + 4 * h;
;               const bool vis = (unsigned)(kc - cs) < 16u;
;               const int idx = (kr - iw + 7) * 31 + (kc - jq + 15);
;               const float bv = biasL[vis ? idx : 0];
;               v = vis ? v + bv : -1e30f;
;             }
;           }
;           s[kb][i] = v; mx = fmaxf(mx, v);
;         }
;       mx = xhalf_max(mx);
;       float mn = m_run;
;       if (__builtin_amdgcn_ballot_w64(mx > m_run) != 0) {
;         mn = fmaxf(m_run, mx);
;         const float al = __builtin_amdgcn_exp2f(m_run - mn);
;         m_run = mn; l_run *= al;
; #pragma unroll
;         for (int i = 0; i < 16; i++) { o[0][i] *= al; o[1][i] *= al; }
;       }
.Lb_nofetch:
	s_mul_i32 s8, s3, 0x3400
	v_add_u32_e32 v0, s8, v172
	ds_read_b128 v[48:51], v0
	ds_read_b128 v[52:55], v0 offset:32
	s_waitcnt vmcnt(10) lgkmcnt(1)
	v_mfma_f32_32x32x16_bf16 v[64:79], v[48:51], v[100:103], v[224:239]
	ds_read_b128 v[48:51], v0 offset:64
	ds_read_b128 v[178:181], v0 offset:6688
	s_waitcnt vmcnt(9) lgkmcnt(2)
	v_mfma_f32_32x32x16_bf16 v[64:79], v[52:55], v[96:99], v[64:79]
	s_waitcnt vmcnt(8) lgkmcnt(1)
	v_mfma_f32_32x32x16_bf16 v[64:79], v[48:51], v[92:95], v[64:79]
	ds_read_b128 v[48:51], v0 offset:96
	s_waitcnt vmcnt(7) lgkmcnt(0)
	v_mfma_f32_32x32x16_bf16 v[64:79], v[48:51], v[88:91], v[64:79]
	ds_read_b128 v[48:51], v0 offset:128
	s_waitcnt vmcnt(6) lgkmcnt(0)
	v_mfma_f32_32x32x16_bf16 v[64:79], v[48:51], v[84:87], v[64:79]
	ds_read_b128 v[48:51], v0 offset:160
	s_waitcnt vmcnt(5) lgkmcnt(0)
	v_mfma_f32_32x32x16_bf16 v[64:79], v[48:51], v[80:83], v[64:79]
	ds_read_b128 v[48:51], v0 offset:6656
	s_waitcnt lgkmcnt(0)
	v_mfma_f32_32x32x16_bf16 v[48:63], v[48:51], v[100:103], v[224:239]
	v_mfma_f32_32x32x16_bf16 v[48:63], v[178:181], v[96:99], v[48:63]
	ds_read_b128 v[178:181], v0 offset:6720
	s_waitcnt lgkmcnt(0)
	v_mfma_f32_32x32x16_bf16 v[48:63], v[178:181], v[92:95], v[48:63]
	ds_read_b128 v[178:181], v0 offset:6752
	s_waitcnt lgkmcnt(0)
	v_mfma_f32_32x32x16_bf16 v[48:63], v[178:181], v[88:91], v[48:63]
	ds_read_b128 v[178:181], v0 offset:6784
	s_waitcnt lgkmcnt(0)
	v_mfma_f32_32x32x16_bf16 v[48:63], v[178:181], v[84:87], v[48:63]
	ds_read_b128 v[178:181], v0 offset:6816
	v_max3_f32 v0, v64, s16, v65
	v_max3_f32 v0, v0, v66, v67
	v_max3_f32 v0, v0, v68, v69
	v_max3_f32 v0, v0, v70, v71
	v_max3_f32 v0, v0, v72, v73
	v_max3_f32 v0, v0, v74, v75
	s_waitcnt lgkmcnt(0)
	v_mfma_f32_32x32x16_bf16 v[48:63], v[178:181], v[80:83], v[48:63]
	v_max3_f32 v0, v0, v76, v77
	v_max3_f32 v0, v0, v78, v79
	s_nop 9
	v_max3_f32 v0, v0, v48, v49
	v_max3_f32 v0, v0, v50, v51
	v_max3_f32 v0, v0, v52, v53
	v_max3_f32 v0, v0, v54, v55
	v_max3_f32 v0, v0, v56, v57
	v_max3_f32 v0, v0, v58, v59
	v_max3_f32 v0, v0, v60, v61
	v_max3_f32 v0, v0, v62, v63
	v_mov_b32_e32 v14, v0
	s_nop 1
	v_permlane32_swap_b32_e32 v0, v14
	v_max_f32_e32 v14, v14, v14
	v_max_f32_e32 v0, v0, v0
	v_max_f32_e32 v0, v0, v14
	v_add_f32_e32 v0, v0, v204
	v_add_f32_e32 v14, 4.0, v145
	v_cmp_gt_f32_e32 vcc, v0, v14
	s_cbranch_vccz .LBB0_894
	v_max_f32_e32 v0, v0, v0
	v_max_f32_e32 v14, v145, v145
	v_max_f32_e32 v14, v14, v0
	v_sub_f32_e32 v0, v145, v14
	v_exp_f32_e32 v0, v0
	v_mov_b32_e32 v145, v14
	v_sub_f32_e32 v15, v14, v204
	v_mov_b32_e32 v204, v14
	v_sub_f32_e32 v224, 0, v14
	v_mov_b32_e32 v225, v224
	v_mov_b32_e32 v226, v224
	v_mov_b32_e32 v227, v224
	v_mov_b32_e32 v228, v224
	v_mov_b32_e32 v229, v224
	v_mov_b32_e32 v230, v224
	v_mov_b32_e32 v231, v224
	v_mov_b32_e32 v232, v224
	v_mov_b32_e32 v233, v224
	v_mov_b32_e32 v234, v224
	v_mov_b32_e32 v235, v224
	v_mov_b32_e32 v236, v224
	v_mov_b32_e32 v237, v224
	v_mov_b32_e32 v238, v224
	v_mov_b32_e32 v239, v224
	v_sub_f32_e32 v64, v64, v15
	v_sub_f32_e32 v65, v65, v15
	v_sub_f32_e32 v66, v66, v15
	v_sub_f32_e32 v67, v67, v15
	v_sub_f32_e32 v68, v68, v15
	v_sub_f32_e32 v69, v69, v15
	v_sub_f32_e32 v70, v70, v15
	v_sub_f32_e32 v71, v71, v15
	v_sub_f32_e32 v72, v72, v15
	v_sub_f32_e32 v73, v73, v15
	v_sub_f32_e32 v74, v74, v15
	v_sub_f32_e32 v75, v75, v15
	v_sub_f32_e32 v76, v76, v15
	v_sub_f32_e32 v77, v77, v15
	v_sub_f32_e32 v78, v78, v15
	v_sub_f32_e32 v79, v79, v15
	v_sub_f32_e32 v48, v48, v15
	v_sub_f32_e32 v49, v49, v15
	v_sub_f32_e32 v50, v50, v15
	v_sub_f32_e32 v51, v51, v15
	v_sub_f32_e32 v52, v52, v15
	v_sub_f32_e32 v53, v53, v15
	v_sub_f32_e32 v54, v54, v15
	v_sub_f32_e32 v55, v55, v15
	v_sub_f32_e32 v56, v56, v15
	v_sub_f32_e32 v57, v57, v15
	v_sub_f32_e32 v58, v58, v15
	v_sub_f32_e32 v59, v59, v15
	v_sub_f32_e32 v60, v60, v15
	v_sub_f32_e32 v61, v61, v15
	v_sub_f32_e32 v62, v62, v15
	v_sub_f32_e32 v63, v63, v15
	v_pk_mul_f32 v[46:47], v[46:47], v[0:1] op_sel_hi:[1,0]
	v_pk_mul_f32 v[44:45], v[44:45], v[0:1] op_sel_hi:[1,0]
	v_pk_mul_f32 v[42:43], v[42:43], v[0:1] op_sel_hi:[1,0]
	v_pk_mul_f32 v[40:41], v[40:41], v[0:1] op_sel_hi:[1,0]
	v_pk_mul_f32 v[38:39], v[38:39], v[0:1] op_sel_hi:[1,0]
	v_pk_mul_f32 v[36:37], v[36:37], v[0:1] op_sel_hi:[1,0]
	v_pk_mul_f32 v[34:35], v[34:35], v[0:1] op_sel_hi:[1,0]
	v_pk_mul_f32 v[32:33], v[32:33], v[0:1] op_sel_hi:[1,0]
	v_pk_mul_f32 v[30:31], v[30:31], v[0:1] op_sel_hi:[1,0]
	v_pk_mul_f32 v[28:29], v[28:29], v[0:1] op_sel_hi:[1,0]
	v_pk_mul_f32 v[26:27], v[26:27], v[0:1] op_sel_hi:[1,0]
	v_pk_mul_f32 v[24:25], v[24:25], v[0:1] op_sel_hi:[1,0]
	v_pk_mul_f32 v[22:23], v[22:23], v[0:1] op_sel_hi:[1,0]
	v_pk_mul_f32 v[20:21], v[20:21], v[0:1] op_sel_hi:[1,0]
	v_pk_mul_f32 v[18:19], v[18:19], v[0:1] op_sel_hi:[1,0]
	v_pk_mul_f32 v[16:17], v[16:17], v[0:1] op_sel_hi:[1,0]
	v_mul_f32_e32 v143, v143, v0
	s_branch .LBB0_894
